# fix: spectrum-store code no longer touches a live register (v102)
# speedup vs baseline: 1.2082x; 1.0040x over previous
; HD float2 cmul(float2 a, float2 b){ return make_float2(a.x*b.x - a.y*b.y, a.x*b.y + a.y*b.x); }
; HD int rev4_14(int p){ unsigned r = __brev((unsigned)p) >> 18; return (int)(((r & 0x2AAAu) >> 1) | ((r & 0x1555u) << 1)); }
; template<bool INV, int LQ, bool BARRIER=true>
; HD void fft_pass(float2* Z, const float2* twA, const float2* twB, int tid){
;     ...
;     int j=tid&(q-1); int base0=((tid>>LQ)<<(LQ+2))+j;
;     float2 w1=make_float2(1.f,0.f), w2=w1, w3=w1;
;     if (LQ>0){ int k=j*tws; w1=cmul(twA[k>>6],twB[k&63]); w2=cmul(w1,w1); w3=cmul(w2,w1); }
;     _Pragma("unroll") for (int i=0;i<8;++i){ int base=base0+i*2048; bf4c<INV,(LQ==0)>(Z,base,base+q,base+2*q,base+3*q,w1,w2,w3); }
;   }
;   if (BARRIER) __syncthreads(); else asm volatile("s_waitcnt lgkmcnt(0)" ::: "memory");
; __device__ __forceinline__ void phase_hyena(KP kp_, int hf){ asm volatile("" : "+s"(kp_)); const Params p=load_params(kp_);
;     ...
;         fft_pass<false,0>(Z,twA,twB,tid);
;     _Pragma("unroll 2") for (int i=0;i<8;++i){ int q0=(tid+512*i)*4; u32x4 h0w, h1w;
;       _Pragma("unroll") for (int m=0;m<4;++m){ int q=q0+m; int k=rev4_14(q);
;         float2 Fk=Z[q], Fn=Z[rev4_14((16384-k)&16383)];
;         f16x2 h0v={(_Float16)(0.5f*nrm0*(Fk.x+Fn.x)),(_Float16)(0.5f*nrm0*(Fk.y-Fn.y))};
.LBB0_1344:
	s_and_b64 vcc, exec, s[12:13]
	s_cbranch_vccz .LBB0_1198
	ds_read_b128 v[0:3], v203
	ds_read_b128 v[4:7], v203 offset:16
	s_mov_b32 s12, 0.5
	s_mov_b32 s13, -0.5
	s_waitcnt lgkmcnt(0)
	v_pk_add_f32 v[12:13], v[0:1], v[4:5]
	v_pk_add_f32 v[14:15], v[2:3], v[6:7]
	v_pk_add_f32 v[0:1], v[0:1], v[4:5] neg_lo:[0,1] neg_hi:[0,1]
	v_pk_add_f32 v[2:3], v[2:3], v[6:7] neg_lo:[0,1] neg_hi:[0,1]
	v_pk_add_f32 v[8:9], v[12:13], v[14:15]
	v_pk_add_f32 v[4:5], v[0:1], v[2:3] op_sel:[0,1] op_sel_hi:[1,0]
	v_pk_add_f32 v[2:3], v[0:1], v[2:3] op_sel:[0,1] op_sel_hi:[1,0] neg_lo:[0,1] neg_hi:[0,1]
	v_mov_b32_e32 v10, v4
	v_mov_b32_e32 v11, v3
	v_pk_add_f32 v[0:1], v[12:13], v[14:15] neg_lo:[0,1] neg_hi:[0,1]
	v_mov_b32_e32 v3, v5
	ds_write_b128 v203, v[8:11]
	ds_write_b128 v203, v[0:3] offset:16
	ds_read_b128 v[0:3], v203 offset:16384
	ds_read_b128 v[4:7], v203 offset:16400
	s_waitcnt lgkmcnt(0)
	v_pk_add_f32 v[12:13], v[0:1], v[4:5]
	v_pk_add_f32 v[14:15], v[2:3], v[6:7]
	v_pk_add_f32 v[0:1], v[0:1], v[4:5] neg_lo:[0,1] neg_hi:[0,1]
	v_pk_add_f32 v[2:3], v[2:3], v[6:7] neg_lo:[0,1] neg_hi:[0,1]
	v_pk_add_f32 v[8:9], v[12:13], v[14:15]
	v_pk_add_f32 v[4:5], v[0:1], v[2:3] op_sel:[0,1] op_sel_hi:[1,0]
	v_pk_add_f32 v[2:3], v[0:1], v[2:3] op_sel:[0,1] op_sel_hi:[1,0] neg_lo:[0,1] neg_hi:[0,1]
	v_mov_b32_e32 v10, v4
	v_mov_b32_e32 v11, v3
	v_pk_add_f32 v[0:1], v[12:13], v[14:15] neg_lo:[0,1] neg_hi:[0,1]
	v_mov_b32_e32 v3, v5
	ds_write_b128 v203, v[8:11] offset:16384
	ds_write_b128 v203, v[0:3] offset:16400
	ds_read_b128 v[0:3], v203 offset:32768
	ds_read_b128 v[4:7], v203 offset:32784
	s_waitcnt lgkmcnt(0)
	v_pk_add_f32 v[12:13], v[0:1], v[4:5]
	v_pk_add_f32 v[14:15], v[2:3], v[6:7]
	v_pk_add_f32 v[0:1], v[0:1], v[4:5] neg_lo:[0,1] neg_hi:[0,1]
	v_pk_add_f32 v[2:3], v[2:3], v[6:7] neg_lo:[0,1] neg_hi:[0,1]
	v_pk_add_f32 v[8:9], v[12:13], v[14:15]
	v_pk_add_f32 v[4:5], v[0:1], v[2:3] op_sel:[0,1] op_sel_hi:[1,0]
	v_pk_add_f32 v[2:3], v[0:1], v[2:3] op_sel:[0,1] op_sel_hi:[1,0] neg_lo:[0,1] neg_hi:[0,1]
	v_mov_b32_e32 v10, v4
	v_mov_b32_e32 v11, v3
	v_pk_add_f32 v[0:1], v[12:13], v[14:15] neg_lo:[0,1] neg_hi:[0,1]
	v_mov_b32_e32 v3, v5
	ds_write_b128 v203, v[8:11] offset:32768
	ds_write_b128 v203, v[0:3] offset:32784
	ds_read_b128 v[0:3], v203 offset:49152
	ds_read_b128 v[4:7], v203 offset:49168
	s_waitcnt lgkmcnt(0)
	v_pk_add_f32 v[12:13], v[0:1], v[4:5]
	v_pk_add_f32 v[14:15], v[2:3], v[6:7]
	v_pk_add_f32 v[0:1], v[0:1], v[4:5] neg_lo:[0,1] neg_hi:[0,1]
	v_pk_add_f32 v[2:3], v[2:3], v[6:7] neg_lo:[0,1] neg_hi:[0,1]
	v_pk_add_f32 v[8:9], v[12:13], v[14:15]
	v_pk_add_f32 v[4:5], v[0:1], v[2:3] op_sel:[0,1] op_sel_hi:[1,0]
	v_pk_add_f32 v[2:3], v[0:1], v[2:3] op_sel:[0,1] op_sel_hi:[1,0] neg_lo:[0,1] neg_hi:[0,1]
	v_mov_b32_e32 v10, v4
	v_mov_b32_e32 v11, v3
	v_pk_add_f32 v[0:1], v[12:13], v[14:15] neg_lo:[0,1] neg_hi:[0,1]
	v_mov_b32_e32 v3, v5
	ds_write_b128 v203, v[8:11] offset:49152
	ds_write_b128 v203, v[0:3] offset:49168
	ds_read_b128 v[0:3], v204
	ds_read_b128 v[4:7], v205
	s_waitcnt lgkmcnt(0)
	v_pk_add_f32 v[12:13], v[0:1], v[4:5]
	v_pk_add_f32 v[14:15], v[2:3], v[6:7]
	v_pk_add_f32 v[0:1], v[0:1], v[4:5] neg_lo:[0,1] neg_hi:[0,1]
	v_pk_add_f32 v[2:3], v[2:3], v[6:7] neg_lo:[0,1] neg_hi:[0,1]
	v_pk_add_f32 v[8:9], v[12:13], v[14:15]
	v_pk_add_f32 v[4:5], v[0:1], v[2:3] op_sel:[0,1] op_sel_hi:[1,0]
	v_pk_add_f32 v[2:3], v[0:1], v[2:3] op_sel:[0,1] op_sel_hi:[1,0] neg_lo:[0,1] neg_hi:[0,1]
	v_mov_b32_e32 v10, v4
	v_mov_b32_e32 v11, v3
	v_pk_add_f32 v[0:1], v[12:13], v[14:15] neg_lo:[0,1] neg_hi:[0,1]
	v_mov_b32_e32 v3, v5
	ds_write_b128 v204, v[8:11]
	ds_write_b128 v205, v[0:3]
	ds_read_b128 v[0:3], v206
	ds_read_b128 v[4:7], v207
	s_waitcnt lgkmcnt(0)
	v_pk_add_f32 v[12:13], v[0:1], v[4:5]
	v_pk_add_f32 v[14:15], v[2:3], v[6:7]
	v_pk_add_f32 v[0:1], v[0:1], v[4:5] neg_lo:[0,1] neg_hi:[0,1]
	v_pk_add_f32 v[2:3], v[2:3], v[6:7] neg_lo:[0,1] neg_hi:[0,1]
	v_pk_add_f32 v[8:9], v[12:13], v[14:15]
	v_pk_add_f32 v[4:5], v[0:1], v[2:3] op_sel:[0,1] op_sel_hi:[1,0]
	v_pk_add_f32 v[2:3], v[0:1], v[2:3] op_sel:[0,1] op_sel_hi:[1,0] neg_lo:[0,1] neg_hi:[0,1]
	v_mov_b32_e32 v10, v4
	v_mov_b32_e32 v11, v3
	v_pk_add_f32 v[0:1], v[12:13], v[14:15] neg_lo:[0,1] neg_hi:[0,1]
	v_mov_b32_e32 v3, v5
	ds_write_b128 v206, v[8:11]
	ds_write_b128 v207, v[0:3]
	ds_read_b128 v[0:3], v208
	ds_read_b128 v[4:7], v209
	s_waitcnt lgkmcnt(0)
	v_pk_add_f32 v[12:13], v[0:1], v[4:5]
	v_pk_add_f32 v[14:15], v[2:3], v[6:7]
	v_pk_add_f32 v[0:1], v[0:1], v[4:5] neg_lo:[0,1] neg_hi:[0,1]
	v_pk_add_f32 v[2:3], v[2:3], v[6:7] neg_lo:[0,1] neg_hi:[0,1]
	v_pk_add_f32 v[8:9], v[12:13], v[14:15]
	v_pk_add_f32 v[4:5], v[0:1], v[2:3] op_sel:[0,1] op_sel_hi:[1,0]
	v_pk_add_f32 v[2:3], v[0:1], v[2:3] op_sel:[0,1] op_sel_hi:[1,0] neg_lo:[0,1] neg_hi:[0,1]
	v_mov_b32_e32 v10, v4
	v_mov_b32_e32 v11, v3
	v_pk_add_f32 v[0:1], v[12:13], v[14:15] neg_lo:[0,1] neg_hi:[0,1]
	v_mov_b32_e32 v3, v5
	ds_write_b128 v208, v[8:11]
	ds_write_b128 v209, v[0:3]
	ds_read_b128 v[0:3], v210
	ds_read_b128 v[4:7], v211
	s_waitcnt lgkmcnt(0)
	v_pk_add_f32 v[12:13], v[0:1], v[4:5]
	v_pk_add_f32 v[14:15], v[2:3], v[6:7]
	v_pk_add_f32 v[0:1], v[0:1], v[4:5] neg_lo:[0,1] neg_hi:[0,1]
	v_pk_add_f32 v[2:3], v[2:3], v[6:7] neg_lo:[0,1] neg_hi:[0,1]
	v_pk_add_f32 v[8:9], v[12:13], v[14:15]
	v_pk_add_f32 v[4:5], v[0:1], v[2:3] op_sel:[0,1] op_sel_hi:[1,0]
	v_pk_add_f32 v[2:3], v[0:1], v[2:3] op_sel:[0,1] op_sel_hi:[1,0] neg_lo:[0,1] neg_hi:[0,1]
	v_pk_add_f32 v[0:1], v[12:13], v[14:15] neg_lo:[0,1] neg_hi:[0,1]
	v_mov_b32_e32 v11, v3
	v_mov_b32_e32 v3, v5
	v_mov_b32_e32 v10, v4
	ds_write_b128 v211, v[0:3]
	v_mul_f32_e32 v2, 0.5, v78
	v_pk_mul_f32 v[0:1], v[78:79], s[12:13] op_sel:[1,0]
	s_mov_b32 s12, 0
	v_mov_b32_e32 v3, v203
	ds_write_b128 v210, v[8:11]
	s_waitcnt lgkmcnt(0)
	s_barrier
; HD int rev4_14(int p){ unsigned r = __brev((unsigned)p) >> 18; return (int)(((r & 0x2AAAu) >> 1) | ((r & 0x1555u) << 1)); }
; __device__ __forceinline__ void phase_hyena(KP kp_, int hf){ asm volatile("" : "+s"(kp_)); const Params p=load_params(kp_);
;     ...
;     _Pragma("unroll 2") for (int i=0;i<8;++i){ int q0=(tid+512*i)*4; u32x4 h0w, h1w;
;       _Pragma("unroll") for (int m=0;m<4;++m){ int q=q0+m; int k=rev4_14(q);
;         float2 Fk=Z[q], Fn=Z[rev4_14((16384-k)&16383)];
;         f16x2 h0v={(_Float16)(0.5f*nrm0*(Fk.x+Fn.x)),(_Float16)(0.5f*nrm0*(Fk.y-Fn.y))};
;         f16x2 h1v={(_Float16)(0.5f*nrm1*(Fk.y+Fn.y)),(_Float16)(-0.5f*nrm1*(Fk.x-Fn.x))};
;         unsigned u0=__builtin_bit_cast(unsigned,h0v), u1=__builtin_bit_cast(unsigned,h1v);
;         h0w[m]=u0; h1w[m]=u1; }
;       *(u32x4*)(H0p+q0)=h0w; *(u32x4*)(H1p+q0)=h1w; }
	v_lshlrev_b32_e32 v70, 5, v154
	v_add_u32_e32 v71, 0x10000, v70
	v_lshlrev_b32_e32 v72, 4, v154
	v_cmp_eq_u32_e64 s[12:13], 0, v154
	v_mov_b32_e32 v68, v154
	v_bfrev_b32_e32 v66, v68
	v_lshrrev_b32_e32 v66, 20, v66
	v_and_b32_e32 v67, 0xaaa, v66
	v_and_b32_e32 v66, 0x555, v66
	v_lshrrev_b32_e32 v67, 1, v67
	v_lshl_or_b32 v69, v66, 1, v67
	v_sub_u32_e32 v69, 0x1000, v69
	v_and_b32_e32 v69, 0xfff, v69
	v_bfrev_b32_e32 v66, v69
	v_lshrrev_b32_e32 v66, 20, v66
	v_and_b32_e32 v67, 0xaaa, v66
	v_and_b32_e32 v66, 0x555, v66
	v_lshrrev_b32_e32 v67, 1, v67
	v_lshl_or_b32 v68, v66, 1, v67
	v_lshlrev_b32_e32 v73, 5, v68
	ds_read_b128 v[4:7], v70 offset:0
	ds_read_b128 v[8:11], v70 offset:16
	ds_read_b128 v[12:15], v73
	ds_read_b128 v[16:19], v73 offset:16
	v_add_u32_e32 v68, 0x200, v154
	v_bfrev_b32_e32 v66, v68
	v_lshrrev_b32_e32 v66, 20, v66
	v_and_b32_e32 v67, 0xaaa, v66
	v_and_b32_e32 v66, 0x555, v66
	v_lshrrev_b32_e32 v67, 1, v67
	v_lshl_or_b32 v69, v66, 1, v67
	v_sub_u32_e32 v69, 0x1000, v69
	v_and_b32_e32 v69, 0xfff, v69
	v_bfrev_b32_e32 v66, v69
	v_lshrrev_b32_e32 v66, 20, v66
	v_and_b32_e32 v67, 0xaaa, v66
	v_and_b32_e32 v66, 0x555, v66
	v_lshrrev_b32_e32 v67, 1, v67
	v_lshl_or_b32 v68, v66, 1, v67
	v_lshlrev_b32_e32 v73, 5, v68
	ds_read_b128 v[20:23], v70 offset:16384
	ds_read_b128 v[24:27], v70 offset:16400
	ds_read_b128 v[58:61], v73
	ds_read_b128 v[62:65], v73 offset:16
	s_waitcnt lgkmcnt(4)
	v_cndmask_b32_e64 v112, v18, v12, s[12:13]
	v_cndmask_b32_e64 v113, v19, v13, s[12:13]
	v_cndmask_b32_e64 v114, v16, v18, s[12:13]
	v_cndmask_b32_e64 v115, v17, v19, s[12:13]
	v_cndmask_b32_e64 v116, v14, v16, s[12:13]
	v_cndmask_b32_e64 v117, v15, v17, s[12:13]
	v_cndmask_b32_e64 v118, v12, v14, s[12:13]
	v_cndmask_b32_e64 v119, v13, v15, s[12:13]
	v_pk_add_f32 v[104:105], v[4:5], v[112:113]
	v_pk_add_f32 v[106:107], v[4:5], v[112:113] neg_lo:[0,1] neg_hi:[0,1]
	v_mul_f32_e32 v108, v2, v104
	v_mul_f32_e32 v109, v2, v107
	v_mul_f32_e32 v110, v0, v105
	v_mul_f32_e32 v111, v1, v106
	v_cvt_pk_f16_f32 v82, v108, v109
	v_cvt_pk_f16_f32 v120, v110, v111
	v_pk_add_f32 v[104:105], v[6:7], v[114:115]
	v_pk_add_f32 v[106:107], v[6:7], v[114:115] neg_lo:[0,1] neg_hi:[0,1]
	v_mul_f32_e32 v108, v2, v104
	v_mul_f32_e32 v109, v2, v107
	v_mul_f32_e32 v110, v0, v105
	v_mul_f32_e32 v111, v1, v106
	v_cvt_pk_f16_f32 v83, v108, v109
	v_cvt_pk_f16_f32 v121, v110, v111
	v_pk_add_f32 v[104:105], v[8:9], v[116:117]
	v_pk_add_f32 v[106:107], v[8:9], v[116:117] neg_lo:[0,1] neg_hi:[0,1]
	v_mul_f32_e32 v108, v2, v104
	v_mul_f32_e32 v109, v2, v107
	v_mul_f32_e32 v110, v0, v105
	v_mul_f32_e32 v111, v1, v106
	v_cvt_pk_f16_f32 v84, v108, v109
	v_cvt_pk_f16_f32 v122, v110, v111
	v_pk_add_f32 v[104:105], v[10:11], v[118:119]
	v_pk_add_f32 v[106:107], v[10:11], v[118:119] neg_lo:[0,1] neg_hi:[0,1]
	v_mul_f32_e32 v108, v2, v104
	v_mul_f32_e32 v109, v2, v107
	v_mul_f32_e32 v110, v0, v105
	v_mul_f32_e32 v111, v1, v106
	v_cvt_pk_f16_f32 v85, v108, v109
	v_cvt_pk_f16_f32 v123, v110, v111
	v_mov_b32_e32 v74, v72
	global_store_dwordx4 v74, v[82:85], s[76:77]
	global_store_dwordx4 v74, v[120:123], s[78:79]
	s_nop 1
	v_add_u32_e32 v68, 0x400, v154
	v_bfrev_b32_e32 v66, v68
	v_lshrrev_b32_e32 v66, 20, v66
	v_and_b32_e32 v67, 0xaaa, v66
	v_and_b32_e32 v66, 0x555, v66
	v_lshrrev_b32_e32 v67, 1, v67
	v_lshl_or_b32 v69, v66, 1, v67
	v_sub_u32_e32 v69, 0x1000, v69
	v_and_b32_e32 v69, 0xfff, v69
	v_bfrev_b32_e32 v66, v69
	v_lshrrev_b32_e32 v66, 20, v66
	v_and_b32_e32 v67, 0xaaa, v66
	v_and_b32_e32 v66, 0x555, v66
	v_lshrrev_b32_e32 v67, 1, v67
	v_lshl_or_b32 v68, v66, 1, v67
	v_lshlrev_b32_e32 v73, 5, v68
	ds_read_b128 v[4:7], v70 offset:32768
	ds_read_b128 v[8:11], v70 offset:32784
	ds_read_b128 v[12:15], v73
	ds_read_b128 v[16:19], v73 offset:16
	s_waitcnt lgkmcnt(4)
	v_pk_add_f32 v[104:105], v[20:21], v[64:65]
	v_pk_add_f32 v[106:107], v[20:21], v[64:65] neg_lo:[0,1] neg_hi:[0,1]
	v_mul_f32_e32 v108, v2, v104
	v_mul_f32_e32 v109, v2, v107
	v_mul_f32_e32 v110, v0, v105
	v_mul_f32_e32 v111, v1, v106
	v_cvt_pk_f16_f32 v82, v108, v109
	v_cvt_pk_f16_f32 v120, v110, v111
	v_pk_add_f32 v[104:105], v[22:23], v[62:63]
	v_pk_add_f32 v[106:107], v[22:23], v[62:63] neg_lo:[0,1] neg_hi:[0,1]
	v_mul_f32_e32 v108, v2, v104
	v_mul_f32_e32 v109, v2, v107
	v_mul_f32_e32 v110, v0, v105
	v_mul_f32_e32 v111, v1, v106
	v_cvt_pk_f16_f32 v83, v108, v109
	v_cvt_pk_f16_f32 v121, v110, v111
	v_pk_add_f32 v[104:105], v[24:25], v[60:61]
	v_pk_add_f32 v[106:107], v[24:25], v[60:61] neg_lo:[0,1] neg_hi:[0,1]
	v_mul_f32_e32 v108, v2, v104
	v_mul_f32_e32 v109, v2, v107
	v_mul_f32_e32 v110, v0, v105
	v_mul_f32_e32 v111, v1, v106
	v_cvt_pk_f16_f32 v84, v108, v109
	v_cvt_pk_f16_f32 v122, v110, v111
	v_pk_add_f32 v[104:105], v[26:27], v[58:59]
	v_pk_add_f32 v[106:107], v[26:27], v[58:59] neg_lo:[0,1] neg_hi:[0,1]
	v_mul_f32_e32 v108, v2, v104
	v_mul_f32_e32 v109, v2, v107
	v_mul_f32_e32 v110, v0, v105
	v_mul_f32_e32 v111, v1, v106
	v_cvt_pk_f16_f32 v85, v108, v109
	v_cvt_pk_f16_f32 v123, v110, v111
	v_add_u32_e32 v74, 0x2000, v72
	global_store_dwordx4 v74, v[82:85], s[76:77]
	global_store_dwordx4 v74, v[120:123], s[78:79]
	s_nop 1
	v_add_u32_e32 v68, 0x600, v154
	v_bfrev_b32_e32 v66, v68
	v_lshrrev_b32_e32 v66, 20, v66
	v_and_b32_e32 v67, 0xaaa, v66
	v_and_b32_e32 v66, 0x555, v66
	v_lshrrev_b32_e32 v67, 1, v67
	v_lshl_or_b32 v69, v66, 1, v67
	v_sub_u32_e32 v69, 0x1000, v69
	v_and_b32_e32 v69, 0xfff, v69
	v_bfrev_b32_e32 v66, v69
	v_lshrrev_b32_e32 v66, 20, v66
	v_and_b32_e32 v67, 0xaaa, v66
	v_and_b32_e32 v66, 0x555, v66
	v_lshrrev_b32_e32 v67, 1, v67
	v_lshl_or_b32 v68, v66, 1, v67
	v_lshlrev_b32_e32 v73, 5, v68
	ds_read_b128 v[20:23], v70 offset:49152
	ds_read_b128 v[24:27], v70 offset:49168
	ds_read_b128 v[58:61], v73
	ds_read_b128 v[62:65], v73 offset:16
	s_waitcnt lgkmcnt(4)
; HD int rev4_14(int p){ unsigned r = __brev((unsigned)p) >> 18; return (int)(((r & 0x2AAAu) >> 1) | ((r & 0x1555u) << 1)); }
; __device__ __forceinline__ void phase_hyena(KP kp_, int hf){ asm volatile("" : "+s"(kp_)); const Params p=load_params(kp_);
;     ...
;     _Pragma("unroll 2") for (int i=0;i<8;++i){ int q0=(tid+512*i)*4; u32x4 h0w, h1w;
;       _Pragma("unroll") for (int m=0;m<4;++m){ int q=q0+m; int k=rev4_14(q);
;         float2 Fk=Z[q], Fn=Z[rev4_14((16384-k)&16383)];
;         f16x2 h0v={(_Float16)(0.5f*nrm0*(Fk.x+Fn.x)),(_Float16)(0.5f*nrm0*(Fk.y-Fn.y))};
;         f16x2 h1v={(_Float16)(0.5f*nrm1*(Fk.y+Fn.y)),(_Float16)(-0.5f*nrm1*(Fk.x-Fn.x))};
;         unsigned u0=__builtin_bit_cast(unsigned,h0v), u1=__builtin_bit_cast(unsigned,h1v);
;         h0w[m]=u0; h1w[m]=u1; }
;       *(u32x4*)(H0p+q0)=h0w; *(u32x4*)(H1p+q0)=h1w; }
	v_pk_add_f32 v[104:105], v[4:5], v[18:19]
	v_pk_add_f32 v[106:107], v[4:5], v[18:19] neg_lo:[0,1] neg_hi:[0,1]
	v_mul_f32_e32 v108, v2, v104
	v_mul_f32_e32 v109, v2, v107
	v_mul_f32_e32 v110, v0, v105
	v_mul_f32_e32 v111, v1, v106
	v_cvt_pk_f16_f32 v82, v108, v109
	v_cvt_pk_f16_f32 v120, v110, v111
	v_pk_add_f32 v[104:105], v[6:7], v[16:17]
	v_pk_add_f32 v[106:107], v[6:7], v[16:17] neg_lo:[0,1] neg_hi:[0,1]
	v_mul_f32_e32 v108, v2, v104
	v_mul_f32_e32 v109, v2, v107
	v_mul_f32_e32 v110, v0, v105
	v_mul_f32_e32 v111, v1, v106
	v_cvt_pk_f16_f32 v83, v108, v109
	v_cvt_pk_f16_f32 v121, v110, v111
	v_pk_add_f32 v[104:105], v[8:9], v[14:15]
	v_pk_add_f32 v[106:107], v[8:9], v[14:15] neg_lo:[0,1] neg_hi:[0,1]
	v_mul_f32_e32 v108, v2, v104
	v_mul_f32_e32 v109, v2, v107
	v_mul_f32_e32 v110, v0, v105
	v_mul_f32_e32 v111, v1, v106
	v_cvt_pk_f16_f32 v84, v108, v109
	v_cvt_pk_f16_f32 v122, v110, v111
	v_pk_add_f32 v[104:105], v[10:11], v[12:13]
	v_pk_add_f32 v[106:107], v[10:11], v[12:13] neg_lo:[0,1] neg_hi:[0,1]
	v_mul_f32_e32 v108, v2, v104
	v_mul_f32_e32 v109, v2, v107
	v_mul_f32_e32 v110, v0, v105
	v_mul_f32_e32 v111, v1, v106
	v_cvt_pk_f16_f32 v85, v108, v109
	v_cvt_pk_f16_f32 v123, v110, v111
	v_add_u32_e32 v74, 0x4000, v72
	global_store_dwordx4 v74, v[82:85], s[76:77]
	global_store_dwordx4 v74, v[120:123], s[78:79]
	s_nop 1
	v_add_u32_e32 v68, 0x800, v154
	v_bfrev_b32_e32 v66, v68
	v_lshrrev_b32_e32 v66, 20, v66
	v_and_b32_e32 v67, 0xaaa, v66
	v_and_b32_e32 v66, 0x555, v66
	v_lshrrev_b32_e32 v67, 1, v67
	v_lshl_or_b32 v69, v66, 1, v67
	v_sub_u32_e32 v69, 0x1000, v69
	v_and_b32_e32 v69, 0xfff, v69
	v_bfrev_b32_e32 v66, v69
	v_lshrrev_b32_e32 v66, 20, v66
	v_and_b32_e32 v67, 0xaaa, v66
	v_and_b32_e32 v66, 0x555, v66
	v_lshrrev_b32_e32 v67, 1, v67
	v_lshl_or_b32 v68, v66, 1, v67
	v_lshlrev_b32_e32 v73, 5, v68
	ds_read_b128 v[4:7], v71 offset:0
	ds_read_b128 v[8:11], v71 offset:16
	ds_read_b128 v[12:15], v73
	ds_read_b128 v[16:19], v73 offset:16
	s_waitcnt lgkmcnt(4)
	v_pk_add_f32 v[104:105], v[20:21], v[64:65]
	v_pk_add_f32 v[106:107], v[20:21], v[64:65] neg_lo:[0,1] neg_hi:[0,1]
	v_mul_f32_e32 v108, v2, v104
	v_mul_f32_e32 v109, v2, v107
	v_mul_f32_e32 v110, v0, v105
	v_mul_f32_e32 v111, v1, v106
	v_cvt_pk_f16_f32 v82, v108, v109
	v_cvt_pk_f16_f32 v120, v110, v111
	v_pk_add_f32 v[104:105], v[22:23], v[62:63]
	v_pk_add_f32 v[106:107], v[22:23], v[62:63] neg_lo:[0,1] neg_hi:[0,1]
	v_mul_f32_e32 v108, v2, v104
	v_mul_f32_e32 v109, v2, v107
	v_mul_f32_e32 v110, v0, v105
	v_mul_f32_e32 v111, v1, v106
	v_cvt_pk_f16_f32 v83, v108, v109
	v_cvt_pk_f16_f32 v121, v110, v111
	v_pk_add_f32 v[104:105], v[24:25], v[60:61]
	v_pk_add_f32 v[106:107], v[24:25], v[60:61] neg_lo:[0,1] neg_hi:[0,1]
	v_mul_f32_e32 v108, v2, v104
	v_mul_f32_e32 v109, v2, v107
	v_mul_f32_e32 v110, v0, v105
	v_mul_f32_e32 v111, v1, v106
	v_cvt_pk_f16_f32 v84, v108, v109
	v_cvt_pk_f16_f32 v122, v110, v111
	v_pk_add_f32 v[104:105], v[26:27], v[58:59]
	v_pk_add_f32 v[106:107], v[26:27], v[58:59] neg_lo:[0,1] neg_hi:[0,1]
	v_mul_f32_e32 v108, v2, v104
	v_mul_f32_e32 v109, v2, v107
	v_mul_f32_e32 v110, v0, v105
	v_mul_f32_e32 v111, v1, v106
	v_cvt_pk_f16_f32 v85, v108, v109
	v_cvt_pk_f16_f32 v123, v110, v111
	v_add_u32_e32 v74, 0x6000, v72
	global_store_dwordx4 v74, v[82:85], s[76:77]
	global_store_dwordx4 v74, v[120:123], s[78:79]
	s_nop 1
	v_add_u32_e32 v68, 0xa00, v154
	v_bfrev_b32_e32 v66, v68
	v_lshrrev_b32_e32 v66, 20, v66
	v_and_b32_e32 v67, 0xaaa, v66
	v_and_b32_e32 v66, 0x555, v66
	v_lshrrev_b32_e32 v67, 1, v67
	v_lshl_or_b32 v69, v66, 1, v67
	v_sub_u32_e32 v69, 0x1000, v69
	v_and_b32_e32 v69, 0xfff, v69
	v_bfrev_b32_e32 v66, v69
	v_lshrrev_b32_e32 v66, 20, v66
	v_and_b32_e32 v67, 0xaaa, v66
	v_and_b32_e32 v66, 0x555, v66
	v_lshrrev_b32_e32 v67, 1, v67
	v_lshl_or_b32 v68, v66, 1, v67
	v_lshlrev_b32_e32 v73, 5, v68
	ds_read_b128 v[20:23], v71 offset:16384
	ds_read_b128 v[24:27], v71 offset:16400
	ds_read_b128 v[58:61], v73
	ds_read_b128 v[62:65], v73 offset:16
	s_waitcnt lgkmcnt(4)
	v_pk_add_f32 v[104:105], v[4:5], v[18:19]
	v_pk_add_f32 v[106:107], v[4:5], v[18:19] neg_lo:[0,1] neg_hi:[0,1]
	v_mul_f32_e32 v108, v2, v104
	v_mul_f32_e32 v109, v2, v107
	v_mul_f32_e32 v110, v0, v105
	v_mul_f32_e32 v111, v1, v106
	v_cvt_pk_f16_f32 v82, v108, v109
	v_cvt_pk_f16_f32 v120, v110, v111
	v_pk_add_f32 v[104:105], v[6:7], v[16:17]
	v_pk_add_f32 v[106:107], v[6:7], v[16:17] neg_lo:[0,1] neg_hi:[0,1]
	v_mul_f32_e32 v108, v2, v104
	v_mul_f32_e32 v109, v2, v107
	v_mul_f32_e32 v110, v0, v105
	v_mul_f32_e32 v111, v1, v106
	v_cvt_pk_f16_f32 v83, v108, v109
	v_cvt_pk_f16_f32 v121, v110, v111
	v_pk_add_f32 v[104:105], v[8:9], v[14:15]
	v_pk_add_f32 v[106:107], v[8:9], v[14:15] neg_lo:[0,1] neg_hi:[0,1]
	v_mul_f32_e32 v108, v2, v104
	v_mul_f32_e32 v109, v2, v107
	v_mul_f32_e32 v110, v0, v105
	v_mul_f32_e32 v111, v1, v106
	v_cvt_pk_f16_f32 v84, v108, v109
	v_cvt_pk_f16_f32 v122, v110, v111
	v_pk_add_f32 v[104:105], v[10:11], v[12:13]
	v_pk_add_f32 v[106:107], v[10:11], v[12:13] neg_lo:[0,1] neg_hi:[0,1]
	v_mul_f32_e32 v108, v2, v104
	v_mul_f32_e32 v109, v2, v107
	v_mul_f32_e32 v110, v0, v105
	v_mul_f32_e32 v111, v1, v106
	v_cvt_pk_f16_f32 v85, v108, v109
	v_cvt_pk_f16_f32 v123, v110, v111
	v_add_u32_e32 v74, 0x8000, v72
	global_store_dwordx4 v74, v[82:85], s[76:77]
	global_store_dwordx4 v74, v[120:123], s[78:79]
	s_nop 1
	v_add_u32_e32 v68, 0xc00, v154
	v_bfrev_b32_e32 v66, v68
	v_lshrrev_b32_e32 v66, 20, v66
	v_and_b32_e32 v67, 0xaaa, v66
	v_and_b32_e32 v66, 0x555, v66
	v_lshrrev_b32_e32 v67, 1, v67
	v_lshl_or_b32 v69, v66, 1, v67
	v_sub_u32_e32 v69, 0x1000, v69
	v_and_b32_e32 v69, 0xfff, v69
	v_bfrev_b32_e32 v66, v69
	v_lshrrev_b32_e32 v66, 20, v66
	v_and_b32_e32 v67, 0xaaa, v66
	v_and_b32_e32 v66, 0x555, v66
	v_lshrrev_b32_e32 v67, 1, v67
	v_lshl_or_b32 v68, v66, 1, v67
	v_lshlrev_b32_e32 v73, 5, v68
	ds_read_b128 v[4:7], v71 offset:32768
	ds_read_b128 v[8:11], v71 offset:32784
	ds_read_b128 v[12:15], v73
	ds_read_b128 v[16:19], v73 offset:16
	s_waitcnt lgkmcnt(4)
; HD int rev4_14(int p){ unsigned r = __brev((unsigned)p) >> 18; return (int)(((r & 0x2AAAu) >> 1) | ((r & 0x1555u) << 1)); }
; __device__ __forceinline__ void phase_hyena(KP kp_, int hf){ asm volatile("" : "+s"(kp_)); const Params p=load_params(kp_);
;     ...
;     _Pragma("unroll 2") for (int i=0;i<8;++i){ int q0=(tid+512*i)*4; u32x4 h0w, h1w;
;       _Pragma("unroll") for (int m=0;m<4;++m){ int q=q0+m; int k=rev4_14(q);
;         float2 Fk=Z[q], Fn=Z[rev4_14((16384-k)&16383)];
;         f16x2 h0v={(_Float16)(0.5f*nrm0*(Fk.x+Fn.x)),(_Float16)(0.5f*nrm0*(Fk.y-Fn.y))};
;         f16x2 h1v={(_Float16)(0.5f*nrm1*(Fk.y+Fn.y)),(_Float16)(-0.5f*nrm1*(Fk.x-Fn.x))};
;         unsigned u0=__builtin_bit_cast(unsigned,h0v), u1=__builtin_bit_cast(unsigned,h1v);
;         h0w[m]=u0; h1w[m]=u1; }
;       *(u32x4*)(H0p+q0)=h0w; *(u32x4*)(H1p+q0)=h1w; }
	v_pk_add_f32 v[104:105], v[20:21], v[64:65]
	v_pk_add_f32 v[106:107], v[20:21], v[64:65] neg_lo:[0,1] neg_hi:[0,1]
	v_mul_f32_e32 v108, v2, v104
	v_mul_f32_e32 v109, v2, v107
	v_mul_f32_e32 v110, v0, v105
	v_mul_f32_e32 v111, v1, v106
	v_cvt_pk_f16_f32 v82, v108, v109
	v_cvt_pk_f16_f32 v120, v110, v111
	v_pk_add_f32 v[104:105], v[22:23], v[62:63]
	v_pk_add_f32 v[106:107], v[22:23], v[62:63] neg_lo:[0,1] neg_hi:[0,1]
	v_mul_f32_e32 v108, v2, v104
	v_mul_f32_e32 v109, v2, v107
	v_mul_f32_e32 v110, v0, v105
	v_mul_f32_e32 v111, v1, v106
	v_cvt_pk_f16_f32 v83, v108, v109
	v_cvt_pk_f16_f32 v121, v110, v111
	v_pk_add_f32 v[104:105], v[24:25], v[60:61]
	v_pk_add_f32 v[106:107], v[24:25], v[60:61] neg_lo:[0,1] neg_hi:[0,1]
	v_mul_f32_e32 v108, v2, v104
	v_mul_f32_e32 v109, v2, v107
	v_mul_f32_e32 v110, v0, v105
	v_mul_f32_e32 v111, v1, v106
	v_cvt_pk_f16_f32 v84, v108, v109
	v_cvt_pk_f16_f32 v122, v110, v111
	v_pk_add_f32 v[104:105], v[26:27], v[58:59]
	v_pk_add_f32 v[106:107], v[26:27], v[58:59] neg_lo:[0,1] neg_hi:[0,1]
	v_mul_f32_e32 v108, v2, v104
	v_mul_f32_e32 v109, v2, v107
	v_mul_f32_e32 v110, v0, v105
	v_mul_f32_e32 v111, v1, v106
	v_cvt_pk_f16_f32 v85, v108, v109
	v_cvt_pk_f16_f32 v123, v110, v111
	v_add_u32_e32 v74, 0xa000, v72
	global_store_dwordx4 v74, v[82:85], s[76:77]
	global_store_dwordx4 v74, v[120:123], s[78:79]
	s_nop 1
	v_add_u32_e32 v68, 0xe00, v154
	v_bfrev_b32_e32 v66, v68
	v_lshrrev_b32_e32 v66, 20, v66
	v_and_b32_e32 v67, 0xaaa, v66
	v_and_b32_e32 v66, 0x555, v66
	v_lshrrev_b32_e32 v67, 1, v67
	v_lshl_or_b32 v69, v66, 1, v67
	v_sub_u32_e32 v69, 0x1000, v69
	v_and_b32_e32 v69, 0xfff, v69
	v_bfrev_b32_e32 v66, v69
	v_lshrrev_b32_e32 v66, 20, v66
	v_and_b32_e32 v67, 0xaaa, v66
	v_and_b32_e32 v66, 0x555, v66
	v_lshrrev_b32_e32 v67, 1, v67
	v_lshl_or_b32 v68, v66, 1, v67
	v_lshlrev_b32_e32 v73, 5, v68
	ds_read_b128 v[20:23], v71 offset:49152
	ds_read_b128 v[24:27], v71 offset:49168
	ds_read_b128 v[58:61], v73
	ds_read_b128 v[62:65], v73 offset:16
	s_waitcnt lgkmcnt(4)
	v_pk_add_f32 v[104:105], v[4:5], v[18:19]
	v_pk_add_f32 v[106:107], v[4:5], v[18:19] neg_lo:[0,1] neg_hi:[0,1]
	v_mul_f32_e32 v108, v2, v104
	v_mul_f32_e32 v109, v2, v107
	v_mul_f32_e32 v110, v0, v105
	v_mul_f32_e32 v111, v1, v106
	v_cvt_pk_f16_f32 v82, v108, v109
	v_cvt_pk_f16_f32 v120, v110, v111
	v_pk_add_f32 v[104:105], v[6:7], v[16:17]
	v_pk_add_f32 v[106:107], v[6:7], v[16:17] neg_lo:[0,1] neg_hi:[0,1]
	v_mul_f32_e32 v108, v2, v104
	v_mul_f32_e32 v109, v2, v107
	v_mul_f32_e32 v110, v0, v105
	v_mul_f32_e32 v111, v1, v106
	v_cvt_pk_f16_f32 v83, v108, v109
	v_cvt_pk_f16_f32 v121, v110, v111
	v_pk_add_f32 v[104:105], v[8:9], v[14:15]
	v_pk_add_f32 v[106:107], v[8:9], v[14:15] neg_lo:[0,1] neg_hi:[0,1]
	v_mul_f32_e32 v108, v2, v104
	v_mul_f32_e32 v109, v2, v107
	v_mul_f32_e32 v110, v0, v105
	v_mul_f32_e32 v111, v1, v106
	v_cvt_pk_f16_f32 v84, v108, v109
	v_cvt_pk_f16_f32 v122, v110, v111
	v_pk_add_f32 v[104:105], v[10:11], v[12:13]
	v_pk_add_f32 v[106:107], v[10:11], v[12:13] neg_lo:[0,1] neg_hi:[0,1]
	v_mul_f32_e32 v108, v2, v104
	v_mul_f32_e32 v109, v2, v107
	v_mul_f32_e32 v110, v0, v105
	v_mul_f32_e32 v111, v1, v106
	v_cvt_pk_f16_f32 v85, v108, v109
	v_cvt_pk_f16_f32 v123, v110, v111
	v_add_u32_e32 v74, 0xc000, v72
	global_store_dwordx4 v74, v[82:85], s[76:77]
	global_store_dwordx4 v74, v[120:123], s[78:79]
	s_nop 1
	s_waitcnt lgkmcnt(0)
	v_pk_add_f32 v[104:105], v[20:21], v[64:65]
	v_pk_add_f32 v[106:107], v[20:21], v[64:65] neg_lo:[0,1] neg_hi:[0,1]
	v_mul_f32_e32 v108, v2, v104
	v_mul_f32_e32 v109, v2, v107
	v_mul_f32_e32 v110, v0, v105
	v_mul_f32_e32 v111, v1, v106
	v_cvt_pk_f16_f32 v82, v108, v109
	v_cvt_pk_f16_f32 v120, v110, v111
	v_pk_add_f32 v[104:105], v[22:23], v[62:63]
	v_pk_add_f32 v[106:107], v[22:23], v[62:63] neg_lo:[0,1] neg_hi:[0,1]
	v_mul_f32_e32 v108, v2, v104
	v_mul_f32_e32 v109, v2, v107
	v_mul_f32_e32 v110, v0, v105
	v_mul_f32_e32 v111, v1, v106
	v_cvt_pk_f16_f32 v83, v108, v109
	v_cvt_pk_f16_f32 v121, v110, v111
	v_pk_add_f32 v[104:105], v[24:25], v[60:61]
	v_pk_add_f32 v[106:107], v[24:25], v[60:61] neg_lo:[0,1] neg_hi:[0,1]
	v_mul_f32_e32 v108, v2, v104
	v_mul_f32_e32 v109, v2, v107
	v_mul_f32_e32 v110, v0, v105
	v_mul_f32_e32 v111, v1, v106
	v_cvt_pk_f16_f32 v84, v108, v109
	v_cvt_pk_f16_f32 v122, v110, v111
	v_pk_add_f32 v[104:105], v[26:27], v[58:59]
	v_pk_add_f32 v[106:107], v[26:27], v[58:59] neg_lo:[0,1] neg_hi:[0,1]
	v_mul_f32_e32 v108, v2, v104
	v_mul_f32_e32 v109, v2, v107
	v_mul_f32_e32 v110, v0, v105
	v_mul_f32_e32 v111, v1, v106
	v_cvt_pk_f16_f32 v85, v108, v109
	v_cvt_pk_f16_f32 v123, v110, v111
	v_add_u32_e32 v74, 0xe000, v72
	global_store_dwordx4 v74, v[82:85], s[76:77]
	global_store_dwordx4 v74, v[120:123], s[78:79]
	s_nop 1
	s_waitcnt vmcnt(0) lgkmcnt(0)
	s_branch .LBB0_1198
